# v43 + 25 dead s_waitcnt lgkmcnt(0) removed in the FFN-in conv region (no LDS op outstanding since the previous full wait)
# baseline (speedup 1.0000x reference)
; __device__ __forceinline__ unsigned cvt_pk_bf16(float lo, float hi) { return pk2(lo, hi); }
;     __device__ __forceinline__ void operator()(f32x4 (&acc)[2][2][4][2], const Unit& u, int wr, int wc, int fr, int fq) const {
;     ...
;                     for (int m = 0; m < 4; ++m) {
;                         const f32x2 pvm = f0 ? (m == 0 ? pe : ps[m == 0 ? 0 : m - 1]) : ps[m];
;                         const f32x2 nvm = f15 ? (m == 3 ? ne : ns[m == 3 ? 3 : m + 1]) : ns[m];
;                         f32x2 cu = w1 * c[m] + bb; cu = w0 * pvm + cu; cu = w2 * nvm + cu;
;                         f32x2 tq = (cu * cu) * cu; tq = tq * 0.044715f + cu;
;                         const f32x2 ea = tq * (-2.3022082f);
;                         f32x2 dn; dn.x = __builtin_amdgcn_exp2f(ea.x); dn.y = __builtin_amdgcn_exp2f(ea.y); dn = dn + 1.0f;
;                         f32x2 rc; rc.x = __builtin_amdgcn_rcpf(dn.x); rc.y = __builtin_amdgcn_rcpf(dn.y);
;                         const f32x2 vv = {acc[ai][1][m][n][2 * p], acc[ai][1][m][n][2 * p + 1]};
;                         const f32x2 o = (cu * rc) * vv;
;                         res[m][2 * p] = o.x; res[m][2 * p + 1] = o.y; }
;                 }
; #pragma unroll
;                 for (int m = 0; m < 4; ++m) { const int j = ai * 128 + wr * 64 + m * 16 + fr;
;                     u32x2 w; w.x = cvt_pk_bf16(res[m][0], res[m][1]); w.y = cvt_pk_bf16(res[m][2], res[m][3]);
;                     if (j >= 1 && j <= 254) *(u32x2*)(act + (size_t)(rowt + j) * FFN + colg + 4 * n) = w; }
.LBB0_435:
	s_and_saveexec_b64 s[12:13], s[40:41]
	s_cbranch_execz .LBB0_437
	v_mov_b32_e32 v250, v182
	v_mov_b32_e32 v251, v182
	s_waitcnt lgkmcnt(0)
	v_cndmask_b32_e64 v193, v240, v193, s[36:37]
	v_cndmask_b32_e64 v192, v103, v192, s[36:37]
	s_waitcnt vmcnt(0)
	v_pk_fma_f32 v[142:143], v[142:143], v[134:135], v[138:139]
	v_pk_mul_f32 v[96:97], v[96:97], v[250:251]
	v_cndmask_b32_e64 v251, v247, v242, s[38:39]
	v_cndmask_b32_e64 v250, v185, v241, s[38:39]
	v_pk_fma_f32 v[142:143], v[126:127], v[192:193], v[142:143]
	s_mov_b32 s24, 0x3d372713
	v_pk_fma_f32 v[142:143], v[130:131], v[250:251], v[142:143]
	s_mov_b32 s66, 0xc0135761
	v_pk_mul_f32 v[192:193], v[142:143], v[142:143]
	v_pk_mul_f32 v[94:95], v[94:95], v[182:183]
	v_pk_mul_f32 v[192:193], v[142:143], v[192:193]
	v_pk_fma_f32 v[144:145], v[144:145], v[136:137], v[140:141]
	v_pk_fma_f32 v[192:193], v[192:193], s[24:25], v[142:143] op_sel_hi:[1,0,1]
	s_movk_i32 s15, 0x1600
	v_pk_mul_f32 v[192:193], v[192:193], s[66:67] op_sel_hi:[1,0]
	s_nop 0
	v_exp_f32_e32 v192, v192
	v_exp_f32_e32 v193, v193
	s_nop 0
	v_pk_add_f32 v[192:193], v[192:193], 1.0 op_sel_hi:[1,0]
	s_nop 0
	v_rcp_f32_e32 v192, v192
	v_rcp_f32_e32 v193, v193
	s_nop 0
	v_pk_mul_f32 v[142:143], v[142:143], v[192:193]
	s_nop 0
	v_pk_mul_f32 v[94:95], v[94:95], v[142:143]
	v_cndmask_b32_e64 v143, v244, v195, s[36:37]
	v_cndmask_b32_e64 v142, v243, v194, s[36:37]
	v_pk_fma_f32 v[142:143], v[128:129], v[142:143], v[144:145]
	v_cndmask_b32_e64 v145, v249, v246, s[38:39]
	v_cndmask_b32_e64 v144, v248, v245, s[38:39]
	v_pk_fma_f32 v[142:143], v[132:133], v[144:145], v[142:143]
	s_nop 0
	v_pk_mul_f32 v[144:145], v[142:143], v[142:143]
	s_nop 0
	v_pk_mul_f32 v[144:145], v[142:143], v[144:145]
	s_nop 0
	v_pk_fma_f32 v[144:145], v[144:145], s[24:25], v[142:143] op_sel_hi:[1,0,1]
	s_nop 0
	v_pk_mul_f32 v[144:145], v[144:145], s[66:67] op_sel_hi:[1,0]
	s_nop 0
	v_exp_f32_e32 v144, v144
	v_exp_f32_e32 v145, v145
	s_nop 0
	v_pk_add_f32 v[144:145], v[144:145], 1.0 op_sel_hi:[1,0]
	s_nop 0
	v_rcp_f32_e32 v144, v144
	v_rcp_f32_e32 v145, v145
	s_nop 0
	v_pk_mul_f32 v[142:143], v[142:143], v[144:145]
	s_nop 0
	v_pk_mul_f32 v[96:97], v[96:97], v[142:143]
	s_nop 0
	v_cvt_pk_bf16_f32 v97, v96, v97
	v_cvt_pk_bf16_f32 v96, v94, v95
	v_mov_b64_e32 v[94:95], s[76:77]
	v_mad_i64_i32 v[94:95], s[66:67], v170, s15, v[94:95]
	v_lshl_add_u64 v[94:95], v[162:163], 1, v[94:95]
	global_store_dwordx2 v[94:95], v[96:97], off
.LBB0_437:
	s_or_b64 exec, exec, s[12:13]
	v_mov_b32_e32 v185, v184
	v_add_u32_e32 v142, s2, v210
	s_and_saveexec_b64 s[12:13], s[42:43]
	s_cbranch_execz .LBB0_439
	v_mov_b32_e32 v94, v184
	v_mov_b32_e32 v95, v184
	v_pk_mul_f32 v[88:89], v[88:89], v[94:95]
	s_waitcnt vmcnt(0)
	v_pk_fma_f32 v[94:95], v[190:191], v[136:137], v[140:141]
	s_waitcnt lgkmcnt(0)
	v_cndmask_b32_e64 v144, v236, v243, s[36:37]
	v_cndmask_b32_e64 v145, v237, v244, s[36:37]
	v_pk_fma_f32 v[96:97], v[188:189], v[134:135], v[138:139]
	v_cndmask_b32_e64 v188, v245, v238, s[38:39]
	v_cndmask_b32_e64 v189, v246, v239, s[38:39]
	v_pk_fma_f32 v[94:95], v[128:129], v[144:145], v[94:95]
	s_mov_b32 s24, 0x3d372713
	v_pk_fma_f32 v[94:95], v[132:133], v[188:189], v[94:95]
	s_mov_b32 s66, 0xc0135761
	v_pk_mul_f32 v[144:145], v[94:95], v[94:95]
	v_pk_mul_f32 v[86:87], v[86:87], v[184:185]
	v_pk_mul_f32 v[144:145], v[94:95], v[144:145]
	s_movk_i32 s15, 0x1600
	v_pk_fma_f32 v[144:145], v[144:145], s[24:25], v[94:95] op_sel_hi:[1,0,1]
	s_nop 0
	v_pk_mul_f32 v[144:145], v[144:145], s[66:67] op_sel_hi:[1,0]
	s_nop 0
	v_exp_f32_e32 v144, v144
	v_exp_f32_e32 v145, v145
	s_nop 0
	v_pk_add_f32 v[144:145], v[144:145], 1.0 op_sel_hi:[1,0]
	s_nop 0
	v_rcp_f32_e32 v144, v144
	v_rcp_f32_e32 v145, v145
	s_nop 0
	v_pk_mul_f32 v[94:95], v[94:95], v[144:145]
	s_nop 0
	v_pk_mul_f32 v[88:89], v[88:89], v[94:95]
	v_cndmask_b32_e64 v94, v232, v103, s[36:37]
	v_cndmask_b32_e64 v95, v233, v240, s[36:37]
	v_cndmask_b32_e64 v144, v241, v234, s[38:39]
	v_cndmask_b32_e64 v145, v242, v235, s[38:39]
	v_pk_fma_f32 v[94:95], v[126:127], v[94:95], v[96:97]
	v_cvt_pk_bf16_f32 v89, v88, v89
	v_pk_fma_f32 v[94:95], v[130:131], v[144:145], v[94:95]
	s_nop 0
	v_pk_mul_f32 v[96:97], v[94:95], v[94:95]
	s_nop 0
	v_pk_mul_f32 v[96:97], v[94:95], v[96:97]
	s_nop 0
	v_pk_fma_f32 v[96:97], v[96:97], s[24:25], v[94:95] op_sel_hi:[1,0,1]
	s_nop 0
	v_pk_mul_f32 v[96:97], v[96:97], s[66:67] op_sel_hi:[1,0]
	s_nop 0
	v_exp_f32_e32 v96, v96
	v_exp_f32_e32 v97, v97
	s_nop 0
	v_pk_add_f32 v[96:97], v[96:97], 1.0 op_sel_hi:[1,0]
	s_nop 0
	v_rcp_f32_e32 v96, v96
	v_rcp_f32_e32 v97, v97
	s_nop 0
	v_pk_mul_f32 v[94:95], v[94:95], v[96:97]
	s_nop 0
	v_pk_mul_f32 v[86:87], v[86:87], v[94:95]
	s_nop 0
	v_cvt_pk_bf16_f32 v88, v86, v87
	v_mov_b64_e32 v[86:87], s[76:77]
	v_mad_i64_i32 v[86:87], s[66:67], v142, s15, v[86:87]
	v_lshl_add_u64 v[86:87], v[162:163], 1, v[86:87]
	global_store_dwordx2 v[86:87], v[88:89], off
; __device__ __forceinline__ unsigned cvt_pk_bf16(float lo, float hi) { return pk2(lo, hi); }
;     __device__ __forceinline__ void operator()(f32x4 (&acc)[2][2][4][2], const Unit& u, int wr, int wc, int fr, int fq) const {
;     ...
;                     for (int m = 0; m < 4; ++m) {
;                         const f32x2 pvm = f0 ? (m == 0 ? pe : ps[m == 0 ? 0 : m - 1]) : ps[m];
;                         const f32x2 nvm = f15 ? (m == 3 ? ne : ns[m == 3 ? 3 : m + 1]) : ns[m];
;                         f32x2 cu = w1 * c[m] + bb; cu = w0 * pvm + cu; cu = w2 * nvm + cu;
;                         f32x2 tq = (cu * cu) * cu; tq = tq * 0.044715f + cu;
;                         const f32x2 ea = tq * (-2.3022082f);
;                         f32x2 dn; dn.x = __builtin_amdgcn_exp2f(ea.x); dn.y = __builtin_amdgcn_exp2f(ea.y); dn = dn + 1.0f;
;                         f32x2 rc; rc.x = __builtin_amdgcn_rcpf(dn.x); rc.y = __builtin_amdgcn_rcpf(dn.y);
;                         const f32x2 vv = {acc[ai][1][m][n][2 * p], acc[ai][1][m][n][2 * p + 1]};
;                         const f32x2 o = (cu * rc) * vv;
;                         res[m][2 * p] = o.x; res[m][2 * p + 1] = o.y; }
;                 }
; #pragma unroll
;                 for (int m = 0; m < 4; ++m) { const int j = ai * 128 + wr * 64 + m * 16 + fr;
;                     u32x2 w; w.x = cvt_pk_bf16(res[m][0], res[m][1]); w.y = cvt_pk_bf16(res[m][2], res[m][3]);
;                     if (j >= 1 && j <= 254) *(u32x2*)(act + (size_t)(rowt + j) * FFN + colg + 4 * n) = w; }
.LBB0_439:
	s_or_b64 exec, exec, s[12:13]
	v_mov_b32_e32 v103, v102
	v_add_u32_e32 v143, s2, v211
	s_and_saveexec_b64 s[12:13], s[44:45]
	s_cbranch_execz .LBB0_441
	v_mov_b32_e32 v86, v102
	v_mov_b32_e32 v87, v102
	v_pk_mul_f32 v[84:85], v[84:85], v[86:87]
	s_waitcnt vmcnt(0)
	v_pk_fma_f32 v[86:87], v[104:105], v[136:137], v[140:141]
	s_waitcnt lgkmcnt(0)
	v_cndmask_b32_e64 v94, v226, v236, s[36:37]
	v_cndmask_b32_e64 v95, v227, v237, s[36:37]
	v_cndmask_b32_e64 v96, v238, v228, s[38:39]
	v_cndmask_b32_e64 v97, v239, v230, s[38:39]
	v_pk_fma_f32 v[86:87], v[128:129], v[94:95], v[86:87]
	s_mov_b32 s24, 0x3d372713
	v_pk_fma_f32 v[86:87], v[132:133], v[96:97], v[86:87]
	s_mov_b32 s66, 0xc0135761
	v_pk_mul_f32 v[94:95], v[86:87], v[86:87]
	v_pk_fma_f32 v[88:89], v[186:187], v[134:135], v[138:139]
	v_pk_mul_f32 v[94:95], v[86:87], v[94:95]
	v_pk_mul_f32 v[82:83], v[82:83], v[102:103]
	v_pk_fma_f32 v[94:95], v[94:95], s[24:25], v[86:87] op_sel_hi:[1,0,1]
	s_movk_i32 s15, 0x1600
	v_pk_mul_f32 v[94:95], v[94:95], s[66:67] op_sel_hi:[1,0]
	s_nop 0
	v_exp_f32_e32 v94, v94
	v_exp_f32_e32 v95, v95
	s_nop 0
	v_pk_add_f32 v[94:95], v[94:95], 1.0 op_sel_hi:[1,0]
	s_nop 0
	v_rcp_f32_e32 v94, v94
	v_rcp_f32_e32 v95, v95
	s_nop 0
	v_pk_mul_f32 v[86:87], v[86:87], v[94:95]
	s_nop 0
	v_pk_mul_f32 v[84:85], v[84:85], v[86:87]
	v_cndmask_b32_e64 v86, v146, v232, s[36:37]
	v_cndmask_b32_e64 v87, v147, v233, s[36:37]
	v_cndmask_b32_e64 v94, v234, v174, s[38:39]
	v_cndmask_b32_e64 v95, v235, v224, s[38:39]
	v_pk_fma_f32 v[86:87], v[126:127], v[86:87], v[88:89]
	v_cvt_pk_bf16_f32 v85, v84, v85
	v_pk_fma_f32 v[86:87], v[130:131], v[94:95], v[86:87]
	s_nop 0
	v_pk_mul_f32 v[88:89], v[86:87], v[86:87]
	s_nop 0
	v_pk_mul_f32 v[88:89], v[86:87], v[88:89]
	s_nop 0
	v_pk_fma_f32 v[88:89], v[88:89], s[24:25], v[86:87] op_sel_hi:[1,0,1]
	s_nop 0
	v_pk_mul_f32 v[88:89], v[88:89], s[66:67] op_sel_hi:[1,0]
	s_nop 0
	v_exp_f32_e32 v88, v88
	v_exp_f32_e32 v89, v89
	s_nop 0
	v_pk_add_f32 v[88:89], v[88:89], 1.0 op_sel_hi:[1,0]
	s_nop 0
	v_rcp_f32_e32 v88, v88
	v_rcp_f32_e32 v89, v89
	s_nop 0
	v_pk_mul_f32 v[86:87], v[86:87], v[88:89]
	s_nop 0
	v_pk_mul_f32 v[82:83], v[82:83], v[86:87]
	s_nop 0
	v_cvt_pk_bf16_f32 v84, v82, v83
	v_mov_b64_e32 v[82:83], s[76:77]
	v_mad_i64_i32 v[82:83], s[66:67], v143, s15, v[82:83]
	v_lshl_add_u64 v[82:83], v[162:163], 1, v[82:83]
	global_store_dwordx2 v[82:83], v[84:85], off
.LBB0_441:
	s_or_b64 exec, exec, s[12:13]
	v_add_u32_e32 v144, s2, v212
	s_and_saveexec_b64 s[12:13], s[46:47]
	s_cbranch_execz .LBB0_443
	v_mov_b32_e32 v82, v176
	v_mov_b32_e32 v83, v176
	v_pk_mul_f32 v[80:81], v[80:81], v[82:83]
	s_waitcnt vmcnt(0)
	v_pk_fma_f32 v[82:83], v[120:121], v[136:137], v[140:141]
	s_waitcnt lgkmcnt(0)
	v_cndmask_b32_e64 v87, v231, v227, s[36:37]
	v_cndmask_b32_e64 v86, v229, v226, s[36:37]
	v_cndmask_b32_e64 v89, v230, v101, s[38:39]
	v_cndmask_b32_e64 v88, v228, v100, s[38:39]
	v_pk_fma_f32 v[82:83], v[128:129], v[86:87], v[82:83]
	s_mov_b32 s24, 0x3d372713
	v_pk_fma_f32 v[82:83], v[132:133], v[88:89], v[82:83]
	s_mov_b32 s66, 0xc0135761
	v_pk_mul_f32 v[86:87], v[82:83], v[82:83]
	v_pk_fma_f32 v[84:85], v[118:119], v[134:135], v[138:139]
	v_pk_mul_f32 v[86:87], v[82:83], v[86:87]
	v_pk_mul_f32 v[78:79], v[78:79], v[176:177]
	v_pk_fma_f32 v[86:87], v[86:87], s[24:25], v[82:83] op_sel_hi:[1,0,1]
	s_movk_i32 s15, 0x1600
	v_pk_mul_f32 v[86:87], v[86:87], s[66:67] op_sel_hi:[1,0]
	s_nop 0
	v_exp_f32_e32 v86, v86
	v_exp_f32_e32 v87, v87
	s_nop 0
	v_pk_add_f32 v[86:87], v[86:87], 1.0 op_sel_hi:[1,0]
	s_nop 0
	v_rcp_f32_e32 v86, v86
	v_rcp_f32_e32 v87, v87
	s_nop 0
	v_pk_mul_f32 v[82:83], v[82:83], v[86:87]
	s_nop 0
	v_pk_mul_f32 v[80:81], v[80:81], v[82:83]
	v_cndmask_b32_e64 v83, v225, v147, s[36:37]
	v_cndmask_b32_e64 v82, v223, v146, s[36:37]
	v_cndmask_b32_e64 v87, v224, v99, s[38:39]
	v_cndmask_b32_e64 v86, v174, v98, s[38:39]
	v_pk_fma_f32 v[82:83], v[126:127], v[82:83], v[84:85]
	v_cvt_pk_bf16_f32 v81, v80, v81
	v_pk_fma_f32 v[82:83], v[130:131], v[86:87], v[82:83]
	s_nop 0
	v_pk_mul_f32 v[84:85], v[82:83], v[82:83]
	s_nop 0
	v_pk_mul_f32 v[84:85], v[82:83], v[84:85]
	s_nop 0
	v_pk_fma_f32 v[84:85], v[84:85], s[24:25], v[82:83] op_sel_hi:[1,0,1]
	s_nop 0
	v_pk_mul_f32 v[84:85], v[84:85], s[66:67] op_sel_hi:[1,0]
	s_nop 0
	v_exp_f32_e32 v84, v84
	v_exp_f32_e32 v85, v85
	s_nop 0
	v_pk_add_f32 v[84:85], v[84:85], 1.0 op_sel_hi:[1,0]
	s_nop 0
	v_rcp_f32_e32 v84, v84
	v_rcp_f32_e32 v85, v85
	s_nop 0
	v_pk_mul_f32 v[82:83], v[82:83], v[84:85]
	s_nop 0
	v_pk_mul_f32 v[78:79], v[78:79], v[82:83]
	s_nop 0
	v_cvt_pk_bf16_f32 v80, v78, v79
	v_mov_b64_e32 v[78:79], s[76:77]
	v_mad_i64_i32 v[78:79], s[66:67], v144, s15, v[78:79]
	v_lshl_add_u64 v[78:79], v[162:163], 1, v[78:79]
	global_store_dwordx2 v[78:79], v[80:81], off

; __device__ __forceinline__ unsigned cvt_pk_bf16(float lo, float hi) { return pk2(lo, hi); }
;     __device__ __forceinline__ void operator()(f32x4 (&acc)[2][2][4][2], const Unit& u, int wr, int wc, int fr, int fq) const {
;     ...
;                     for (int m = 0; m < 4; ++m) {
;                         const f32x2 pvm = f0 ? (m == 0 ? pe : ps[m == 0 ? 0 : m - 1]) : ps[m];
;                         const f32x2 nvm = f15 ? (m == 3 ? ne : ns[m == 3 ? 3 : m + 1]) : ns[m];
;                         f32x2 cu = w1 * c[m] + bb; cu = w0 * pvm + cu; cu = w2 * nvm + cu;
;                         f32x2 tq = (cu * cu) * cu; tq = tq * 0.044715f + cu;
;                         const f32x2 ea = tq * (-2.3022082f);
;                         f32x2 dn; dn.x = __builtin_amdgcn_exp2f(ea.x); dn.y = __builtin_amdgcn_exp2f(ea.y); dn = dn + 1.0f;
;                         f32x2 rc; rc.x = __builtin_amdgcn_rcpf(dn.x); rc.y = __builtin_amdgcn_rcpf(dn.y);
;                         const f32x2 vv = {acc[ai][1][m][n][2 * p], acc[ai][1][m][n][2 * p + 1]};
;                         const f32x2 o = (cu * rc) * vv;
;                         res[m][2 * p] = o.x; res[m][2 * p + 1] = o.y; }
;                 }
; #pragma unroll
;                 for (int m = 0; m < 4; ++m) { const int j = ai * 128 + wr * 64 + m * 16 + fr;
;                     u32x2 w; w.x = cvt_pk_bf16(res[m][0], res[m][1]); w.y = cvt_pk_bf16(res[m][2], res[m][3]);
;                     if (j >= 1 && j <= 254) *(u32x2*)(act + (size_t)(rowt + j) * FFN + colg + 4 * n) = w; }
.LBB0_451:
	s_and_saveexec_b64 s[12:13], s[40:41]
	s_movk_i32 s64, 0x6000
	v_readlane_b32 s65, v255, 9
	s_cbranch_execz .LBB0_455
	s_waitcnt lgkmcnt(0)
	v_cndmask_b32_e64 v105, v174, v105, s[36:37]
	v_cndmask_b32_e64 v104, v147, v104, s[36:37]
	s_waitcnt vmcnt(0)
	v_pk_fma_f32 v[122:123], v[122:123], v[86:87], v[94:95]
	v_mov_b32_e32 v224, v182
	v_mov_b32_e32 v225, v182
	v_pk_mul_f32 v[62:63], v[62:63], v[182:183]
	v_cndmask_b32_e64 v183, v193, v187, s[38:39]
	v_cndmask_b32_e64 v182, v192, v186, s[38:39]
	v_pk_fma_f32 v[104:105], v[78:79], v[104:105], v[122:123]
	s_mov_b32 s24, 0x3d372713
	v_pk_fma_f32 v[104:105], v[82:83], v[182:183], v[104:105]
	s_mov_b32 s62, 0xc0135761
	v_pk_mul_f32 v[122:123], v[104:105], v[104:105]
	v_pk_fma_f32 v[124:125], v[124:125], v[88:89], v[96:97]
	v_pk_mul_f32 v[122:123], v[104:105], v[122:123]
	v_pk_mul_f32 v[64:65], v[64:65], v[224:225]
	v_pk_fma_f32 v[122:123], v[122:123], s[24:25], v[104:105] op_sel_hi:[1,0,1]
	s_movk_i32 s15, 0x1600
	v_pk_mul_f32 v[122:123], v[122:123], s[62:63] op_sel_hi:[1,0]
	s_nop 0
	v_exp_f32_e32 v122, v122
	v_exp_f32_e32 v123, v123
	s_nop 0
	v_pk_add_f32 v[122:123], v[122:123], 1.0 op_sel_hi:[1,0]
	s_nop 0
	v_rcp_f32_e32 v122, v122
	v_rcp_f32_e32 v123, v123
	s_nop 0
	v_pk_mul_f32 v[104:105], v[104:105], v[122:123]
	s_nop 0
	v_pk_mul_f32 v[62:63], v[62:63], v[104:105]
	v_cndmask_b32_e64 v105, v189, v119, s[36:37]
	v_cndmask_b32_e64 v104, v188, v118, s[36:37]
	v_pk_fma_f32 v[104:105], v[80:81], v[104:105], v[124:125]
	v_cndmask_b32_e64 v119, v195, v191, s[38:39]
	v_cndmask_b32_e64 v118, v194, v190, s[38:39]
	v_pk_fma_f32 v[104:105], v[84:85], v[118:119], v[104:105]
	s_nop 0
	v_pk_mul_f32 v[118:119], v[104:105], v[104:105]
	s_nop 0
	v_pk_mul_f32 v[118:119], v[104:105], v[118:119]
	s_nop 0
	v_pk_fma_f32 v[118:119], v[118:119], s[24:25], v[104:105] op_sel_hi:[1,0,1]
	s_nop 0
	v_pk_mul_f32 v[118:119], v[118:119], s[62:63] op_sel_hi:[1,0]
	s_nop 0
	v_exp_f32_e32 v118, v118
	v_exp_f32_e32 v119, v119
	s_nop 0
	v_pk_add_f32 v[118:119], v[118:119], 1.0 op_sel_hi:[1,0]
	s_nop 0
	v_rcp_f32_e32 v118, v118
	v_rcp_f32_e32 v119, v119
	s_nop 0
	v_pk_mul_f32 v[104:105], v[104:105], v[118:119]
	s_nop 0
	v_pk_mul_f32 v[64:65], v[64:65], v[104:105]
	s_nop 0
	v_cvt_pk_bf16_f32 v65, v64, v65
	v_cvt_pk_bf16_f32 v64, v62, v63
	v_mov_b64_e32 v[62:63], s[76:77]
	v_mad_i64_i32 v[62:63], s[62:63], v170, s15, v[62:63]
	v_lshl_add_u64 v[62:63], v[162:163], 1, v[62:63]
	global_store_dwordx2 v[62:63], v[64:65], off offset:8
	s_or_b64 exec, exec, s[12:13]
	s_and_saveexec_b64 s[12:13], s[42:43]
	s_cbranch_execnz .LBB0_456

; __device__ __forceinline__ unsigned cvt_pk_bf16(float lo, float hi) { return pk2(lo, hi); }
;     __device__ __forceinline__ void operator()(f32x4 (&acc)[2][2][4][2], const Unit& u, int wr, int wc, int fr, int fq) const {
;     ...
;                     for (int m = 0; m < 4; ++m) {
;                         const f32x2 pvm = f0 ? (m == 0 ? pe : ps[m == 0 ? 0 : m - 1]) : ps[m];
;                         const f32x2 nvm = f15 ? (m == 3 ? ne : ns[m == 3 ? 3 : m + 1]) : ns[m];
;                         f32x2 cu = w1 * c[m] + bb; cu = w0 * pvm + cu; cu = w2 * nvm + cu;
;                         f32x2 tq = (cu * cu) * cu; tq = tq * 0.044715f + cu;
;                         const f32x2 ea = tq * (-2.3022082f);
;                         f32x2 dn; dn.x = __builtin_amdgcn_exp2f(ea.x); dn.y = __builtin_amdgcn_exp2f(ea.y); dn = dn + 1.0f;
;                         f32x2 rc; rc.x = __builtin_amdgcn_rcpf(dn.x); rc.y = __builtin_amdgcn_rcpf(dn.y);
;                         const f32x2 vv = {acc[ai][1][m][n][2 * p], acc[ai][1][m][n][2 * p + 1]};
;                         const f32x2 o = (cu * rc) * vv;
;                         res[m][2 * p] = o.x; res[m][2 * p + 1] = o.y; }
;                 }
; #pragma unroll
;                 for (int m = 0; m < 4; ++m) { const int j = ai * 128 + wr * 64 + m * 16 + fr;
;                     u32x2 w; w.x = cvt_pk_bf16(res[m][0], res[m][1]); w.y = cvt_pk_bf16(res[m][2], res[m][3]);
;                     if (j >= 1 && j <= 254) *(u32x2*)(act + (size_t)(rowt + j) * FFN + colg + 4 * n) = w; }
.LBB0_454:
	v_mov_b32_e32 v58, v102
	v_mov_b32_e32 v59, v102
	v_pk_mul_f32 v[56:57], v[56:57], v[58:59]
	s_waitcnt vmcnt(0)
	v_pk_fma_f32 v[58:59], v[72:73], v[88:89], v[96:97]
	s_waitcnt lgkmcnt(0)
	v_cndmask_b32_e64 v62, v130, v140, s[36:37]
	v_cndmask_b32_e64 v63, v131, v141, s[36:37]
	v_cndmask_b32_e64 v64, v145, v132, s[38:39]
	v_cndmask_b32_e64 v65, v146, v134, s[38:39]
	v_pk_fma_f32 v[58:59], v[80:81], v[62:63], v[58:59]
	s_mov_b32 s24, 0x3d372713
	v_pk_fma_f32 v[58:59], v[84:85], v[64:65], v[58:59]
	s_mov_b32 s62, 0xc0135761
	v_pk_mul_f32 v[62:63], v[58:59], v[58:59]
	v_pk_fma_f32 v[60:61], v[70:71], v[86:87], v[94:95]
	v_pk_mul_f32 v[62:63], v[58:59], v[62:63]
	v_pk_mul_f32 v[54:55], v[54:55], v[102:103]
	v_pk_fma_f32 v[62:63], v[62:63], s[24:25], v[58:59] op_sel_hi:[1,0,1]
	s_movk_i32 s15, 0x1600
	v_pk_mul_f32 v[62:63], v[62:63], s[62:63] op_sel_hi:[1,0]
	s_nop 0
	v_exp_f32_e32 v62, v62
	v_exp_f32_e32 v63, v63
	s_nop 0
	v_pk_add_f32 v[62:63], v[62:63], 1.0 op_sel_hi:[1,0]
	s_nop 0
	v_rcp_f32_e32 v62, v62
	v_rcp_f32_e32 v63, v63
	s_nop 0
	v_pk_mul_f32 v[58:59], v[58:59], v[62:63]
	s_nop 0
	v_pk_mul_f32 v[56:57], v[56:57], v[58:59]
	v_cndmask_b32_e64 v58, v120, v136, s[36:37]
	v_cndmask_b32_e64 v59, v121, v137, s[36:37]
	v_cndmask_b32_e64 v62, v138, v126, s[38:39]
	v_cndmask_b32_e64 v63, v139, v128, s[38:39]
	v_pk_fma_f32 v[58:59], v[78:79], v[58:59], v[60:61]
	v_cvt_pk_bf16_f32 v57, v56, v57
	v_pk_fma_f32 v[58:59], v[82:83], v[62:63], v[58:59]
	s_nop 0
	v_pk_mul_f32 v[60:61], v[58:59], v[58:59]
	s_nop 0
	v_pk_mul_f32 v[60:61], v[58:59], v[60:61]
	s_nop 0
	v_pk_fma_f32 v[60:61], v[60:61], s[24:25], v[58:59] op_sel_hi:[1,0,1]
	s_nop 0
	v_pk_mul_f32 v[60:61], v[60:61], s[62:63] op_sel_hi:[1,0]
	s_nop 0
	v_exp_f32_e32 v60, v60
	v_exp_f32_e32 v61, v61
	s_nop 0
	v_pk_add_f32 v[60:61], v[60:61], 1.0 op_sel_hi:[1,0]
	s_nop 0
	v_rcp_f32_e32 v60, v60
	v_rcp_f32_e32 v61, v61
	s_nop 0
	v_pk_mul_f32 v[58:59], v[58:59], v[60:61]
	s_nop 0
	v_pk_mul_f32 v[54:55], v[54:55], v[58:59]
	s_nop 0
	v_cvt_pk_bf16_f32 v56, v54, v55
	v_mov_b64_e32 v[54:55], s[76:77]
	v_mad_i64_i32 v[54:55], s[62:63], v143, s15, v[54:55]
	v_lshl_add_u64 v[54:55], v[162:163], 1, v[54:55]
	global_store_dwordx2 v[54:55], v[56:57], off offset:8
	s_or_b64 exec, exec, s[12:13]
	s_and_saveexec_b64 s[12:13], s[46:47]
	s_cbranch_execnz .LBB0_458
	s_branch .LBB0_459

; __device__ __forceinline__ unsigned cvt_pk_bf16(float lo, float hi) { return pk2(lo, hi); }
;     __device__ __forceinline__ void operator()(f32x4 (&acc)[2][2][4][2], const Unit& u, int wr, int wc, int fr, int fq) const {
;     ...
;                     for (int m = 0; m < 4; ++m) {
;                         const f32x2 pvm = f0 ? (m == 0 ? pe : ps[m == 0 ? 0 : m - 1]) : ps[m];
;                         const f32x2 nvm = f15 ? (m == 3 ? ne : ns[m == 3 ? 3 : m + 1]) : ns[m];
;                         f32x2 cu = w1 * c[m] + bb; cu = w0 * pvm + cu; cu = w2 * nvm + cu;
;                         f32x2 tq = (cu * cu) * cu; tq = tq * 0.044715f + cu;
;                         const f32x2 ea = tq * (-2.3022082f);
;                         f32x2 dn; dn.x = __builtin_amdgcn_exp2f(ea.x); dn.y = __builtin_amdgcn_exp2f(ea.y); dn = dn + 1.0f;
;                         f32x2 rc; rc.x = __builtin_amdgcn_rcpf(dn.x); rc.y = __builtin_amdgcn_rcpf(dn.y);
;                         const f32x2 vv = {acc[ai][1][m][n][2 * p], acc[ai][1][m][n][2 * p + 1]};
;                         const f32x2 o = (cu * rc) * vv;
;                         res[m][2 * p] = o.x; res[m][2 * p + 1] = o.y; }
;                 }
; #pragma unroll
;                 for (int m = 0; m < 4; ++m) { const int j = ai * 128 + wr * 64 + m * 16 + fr;
;                     u32x2 w; w.x = cvt_pk_bf16(res[m][0], res[m][1]); w.y = cvt_pk_bf16(res[m][2], res[m][3]);
;                     if (j >= 1 && j <= 254) *(u32x2*)(act + (size_t)(rowt + j) * FFN + colg + 4 * n) = w; }
.LBB0_456:
	v_mov_b32_e32 v62, v184
	v_mov_b32_e32 v63, v184
	v_pk_mul_f32 v[60:61], v[60:61], v[62:63]
	s_waitcnt vmcnt(0)
	v_pk_fma_f32 v[62:63], v[100:101], v[88:89], v[96:97]
	v_pk_fma_f32 v[64:65], v[98:99], v[86:87], v[94:95]
	s_waitcnt lgkmcnt(0)
	v_cndmask_b32_e64 v98, v140, v188, s[36:37]
	v_cndmask_b32_e64 v99, v141, v189, s[36:37]
	v_cndmask_b32_e64 v100, v190, v145, s[38:39]
	v_cndmask_b32_e64 v101, v191, v146, s[38:39]
	v_pk_fma_f32 v[62:63], v[80:81], v[98:99], v[62:63]
	s_mov_b32 s24, 0x3d372713
	v_pk_fma_f32 v[62:63], v[84:85], v[100:101], v[62:63]
	s_mov_b32 s62, 0xc0135761
	v_pk_mul_f32 v[98:99], v[62:63], v[62:63]
	v_pk_mul_f32 v[58:59], v[58:59], v[184:185]
	v_pk_mul_f32 v[98:99], v[62:63], v[98:99]
	s_movk_i32 s15, 0x1600
	v_pk_fma_f32 v[98:99], v[98:99], s[24:25], v[62:63] op_sel_hi:[1,0,1]
	s_nop 0
	v_pk_mul_f32 v[98:99], v[98:99], s[62:63] op_sel_hi:[1,0]
	s_nop 0
	v_exp_f32_e32 v98, v98
	v_exp_f32_e32 v99, v99
	s_nop 0
	v_pk_add_f32 v[98:99], v[98:99], 1.0 op_sel_hi:[1,0]
	s_nop 0
	v_rcp_f32_e32 v98, v98
	v_rcp_f32_e32 v99, v99
	s_nop 0
	v_pk_mul_f32 v[62:63], v[62:63], v[98:99]
	s_nop 0
	v_pk_mul_f32 v[60:61], v[60:61], v[62:63]
	v_cndmask_b32_e64 v62, v136, v147, s[36:37]
	v_cndmask_b32_e64 v63, v137, v174, s[36:37]
	v_cndmask_b32_e64 v98, v186, v138, s[38:39]
	v_cndmask_b32_e64 v99, v187, v139, s[38:39]
	v_pk_fma_f32 v[62:63], v[78:79], v[62:63], v[64:65]
	v_cvt_pk_bf16_f32 v61, v60, v61
	v_pk_fma_f32 v[62:63], v[82:83], v[98:99], v[62:63]
	s_nop 0
	v_pk_mul_f32 v[64:65], v[62:63], v[62:63]
	s_nop 0
	v_pk_mul_f32 v[64:65], v[62:63], v[64:65]
	s_nop 0
	v_pk_fma_f32 v[64:65], v[64:65], s[24:25], v[62:63] op_sel_hi:[1,0,1]
	s_nop 0
	v_pk_mul_f32 v[64:65], v[64:65], s[62:63] op_sel_hi:[1,0]
	s_nop 0
	v_exp_f32_e32 v64, v64
	v_exp_f32_e32 v65, v65
	s_nop 0
	v_pk_add_f32 v[64:65], v[64:65], 1.0 op_sel_hi:[1,0]
	s_nop 0
	v_rcp_f32_e32 v64, v64
	v_rcp_f32_e32 v65, v65
	s_nop 0
	v_pk_mul_f32 v[62:63], v[62:63], v[64:65]
	s_nop 0
	v_pk_mul_f32 v[58:59], v[58:59], v[62:63]
	s_nop 0
	v_cvt_pk_bf16_f32 v60, v58, v59
	v_mov_b64_e32 v[58:59], s[76:77]
	v_mad_i64_i32 v[58:59], s[62:63], v142, s15, v[58:59]
	v_lshl_add_u64 v[58:59], v[162:163], 1, v[58:59]
	global_store_dwordx2 v[58:59], v[60:61], off offset:8
	s_or_b64 exec, exec, s[12:13]
	s_and_saveexec_b64 s[12:13], s[44:45]
	s_cbranch_execnz .LBB0_454

;     __device__ __forceinline__ void operator()(f32x4 (&acc)[2][2][4][2], const Unit& u, int wr, int wc, int fr, int fq) const {
;     ...
;                 const f32x4 w0v = *(const f32x4*)(cw + colg + 4 * n), w1v = *(const f32x4*)(cw + FFN + colg + 4 * n), w2v = *(const f32x4*)(cw + 2 * FFN + colg + 4 * n), cbv = *(const f32x4*)(cb + colg + 4 * n);
;                 f32x4 res[4];
; #pragma unroll
;                 for (int p = 0; p < 2; ++p) {
;                     const f32x2 w0 = {w0v[2 * p], w0v[2 * p + 1]}, w1 = {w1v[2 * p], w1v[2 * p + 1]}, w2 = {w2v[2 * p], w2v[2 * p + 1]}, bb = {cbv[2 * p], cbv[2 * p + 1]};
;                     f32x2 c[4], ps[4], ns[4];
; #pragma unroll
;                     for (int m = 0; m < 4; ++m) { c[m] = (f32x2){acc[ai][0][m][n][2 * p], acc[ai][0][m][n][2 * p + 1]};
;                         ps[m] = (f32x2){__shfl(c[m].x, lprev), __shfl(c[m].y, lprev)}; ns[m] = (f32x2){__shfl(c[m].x, lnext), __shfl(c[m].y, lnext)}; }
;                     f32x2 pe = {0.f, 0.f}, ne = {0.f, 0.f};
;                     if (blk > 0) pe = (f32x2){edgeL[(blk - 1) * 128 + colw + 4 * n + 2 * p], edgeL[(blk - 1) * 128 + colw + 4 * n + 2 * p + 1]};
;                     if (blk < 3) ne = (f32x2){edgeF[(blk + 1) * 128 + colw + 4 * n + 2 * p], edgeF[(blk + 1) * 128 + colw + 4 * n + 2 * p + 1]};
; #pragma unroll
;                     for (int m = 0; m < 4; ++m) {
;                         const f32x2 pvm = f0 ? (m == 0 ? pe : ps[m == 0 ? 0 : m - 1]) : ps[m];
;                         const f32x2 nvm = f15 ? (m == 3 ? ne : ns[m == 3 ? 3 : m + 1]) : ns[m];
;                         f32x2 cu = w1 * c[m] + bb; cu = w0 * pvm + cu; cu = w2 * nvm + cu;
;                         f32x2 tq = (cu * cu) * cu; tq = tq * 0.044715f + cu;
;                         const f32x2 ea = tq * (-2.3022082f);
;                         f32x2 dn; dn.x = __builtin_amdgcn_exp2f(ea.x); dn.y = __builtin_amdgcn_exp2f(ea.y); dn = dn + 1.0f;
;                         f32x2 rc; rc.x = __builtin_amdgcn_rcpf(dn.x); rc.y = __builtin_amdgcn_rcpf(dn.y);
;                         const f32x2 vv = {acc[ai][1][m][n][2 * p], acc[ai][1][m][n][2 * p + 1]};
;                         const f32x2 o = (cu * rc) * vv;
.LBB0_458:
	v_mov_b32_e32 v54, v176
	v_mov_b32_e32 v55, v176
	v_pk_mul_f32 v[52:53], v[52:53], v[54:55]
	s_waitcnt vmcnt(0)
	v_pk_fma_f32 v[54:55], v[116:117], v[88:89], v[96:97]
	s_waitcnt lgkmcnt(0)
	v_cndmask_b32_e64 v59, v135, v131, s[36:37]
	v_cndmask_b32_e64 v58, v133, v130, s[36:37]
	v_cndmask_b32_e64 v61, v134, v69, s[38:39]
	v_cndmask_b32_e64 v60, v132, v68, s[38:39]
	v_pk_fma_f32 v[54:55], v[80:81], v[58:59], v[54:55]
	s_mov_b32 s24, 0x3d372713
	v_pk_fma_f32 v[54:55], v[84:85], v[60:61], v[54:55]
	s_mov_b32 s62, 0xc0135761
	v_pk_mul_f32 v[58:59], v[54:55], v[54:55]
	v_pk_fma_f32 v[56:57], v[114:115], v[86:87], v[94:95]
	v_pk_mul_f32 v[58:59], v[54:55], v[58:59]
	v_pk_mul_f32 v[50:51], v[50:51], v[176:177]
	v_pk_fma_f32 v[58:59], v[58:59], s[24:25], v[54:55] op_sel_hi:[1,0,1]
	s_movk_i32 s15, 0x1600
	v_pk_mul_f32 v[58:59], v[58:59], s[62:63] op_sel_hi:[1,0]
	s_nop 0
	v_exp_f32_e32 v58, v58
	v_exp_f32_e32 v59, v59
	s_nop 0
	v_pk_add_f32 v[58:59], v[58:59], 1.0 op_sel_hi:[1,0]
	s_nop 0
	v_rcp_f32_e32 v58, v58
	v_rcp_f32_e32 v59, v59
	s_nop 0
	v_pk_mul_f32 v[54:55], v[54:55], v[58:59]
	s_nop 0
	v_pk_mul_f32 v[52:53], v[52:53], v[54:55]
	v_cndmask_b32_e64 v55, v129, v121, s[36:37]
	v_cndmask_b32_e64 v54, v127, v120, s[36:37]
	v_cndmask_b32_e64 v59, v128, v67, s[38:39]
	v_cndmask_b32_e64 v58, v126, v66, s[38:39]
	v_pk_fma_f32 v[54:55], v[78:79], v[54:55], v[56:57]
	v_cvt_pk_bf16_f32 v53, v52, v53
	v_pk_fma_f32 v[54:55], v[82:83], v[58:59], v[54:55]
	s_nop 0
	v_pk_mul_f32 v[56:57], v[54:55], v[54:55]
	s_nop 0
	v_pk_mul_f32 v[56:57], v[54:55], v[56:57]
	s_nop 0
	v_pk_fma_f32 v[56:57], v[56:57], s[24:25], v[54:55] op_sel_hi:[1,0,1]
	s_nop 0
	v_pk_mul_f32 v[56:57], v[56:57], s[62:63] op_sel_hi:[1,0]
	s_nop 0
	v_exp_f32_e32 v56, v56
	v_exp_f32_e32 v57, v57
	s_nop 0
	v_pk_add_f32 v[56:57], v[56:57], 1.0 op_sel_hi:[1,0]
	s_nop 0
	v_rcp_f32_e32 v56, v56
	v_rcp_f32_e32 v57, v57
	s_nop 0
	v_pk_mul_f32 v[54:55], v[54:55], v[56:57]
	s_nop 0
	v_pk_mul_f32 v[50:51], v[50:51], v[54:55]
	s_nop 0
	v_cvt_pk_bf16_f32 v52, v50, v51
	v_mov_b64_e32 v[50:51], s[76:77]
	v_mad_i64_i32 v[50:51], s[62:63], v144, s15, v[50:51]
	v_lshl_add_u64 v[50:51], v[162:163], 1, v[50:51]
	global_store_dwordx2 v[50:51], v[52:53], off offset:8
.LBB0_459:
	s_or_b64 exec, exec, s[12:13]
	global_load_dwordx4 v[50:53], v[166:167], off
	global_load_dwordx4 v[58:61], v[178:179], off
	global_load_dwordx4 v[54:57], v[180:181], off
	global_load_dwordx4 v[62:65], v[168:169], off
	s_waitcnt lgkmcnt(0)
	v_mul_f32_e32 v66, 0x4b800000, v172
	v_cndmask_b32_e64 v66, v172, v66, s[58:59]
	v_rsq_f32_e32 v66, v66
	v_mul_f32_e32 v67, 0x4b800000, v175
	v_cndmask_b32_e64 v67, v175, v67, s[60:61]
	v_rsq_f32_e32 v67, v67
	v_mul_f32_e32 v68, 0x45800000, v66
	v_cndmask_b32_e64 v66, v66, v68, s[58:59]
	v_mov_b32_dpp v115, v111 row_ror:1 row_mask:0xf bank_mask:0xf
	v_pk_mul_f32 v[70:71], v[46:47], v[66:67] op_sel_hi:[1,0]
	v_mul_f32_e32 v46, 0x45800000, v67
	v_cndmask_b32_e64 v46, v67, v46, s[60:61]
	v_pk_mul_f32 v[68:69], v[42:43], v[46:47] op_sel_hi:[1,0]
	v_mov_b32_dpp v47, v110 row_ror:1 row_mask:0xf bank_mask:0xf
	v_mov_b32_dpp v67, v110 row_ror:15 row_mask:0xf bank_mask:0xf
	v_mov_b32_dpp v122, v111 row_ror:15 row_mask:0xf bank_mask:0xf
	v_mov_b32_dpp v99, v70 row_ror:1 row_mask:0xf bank_mask:0xf
	v_mov_b32_dpp v100, v71 row_ror:1 row_mask:0xf bank_mask:0xf
	v_mov_b32_dpp v116, v70 row_ror:15 row_mask:0xf bank_mask:0xf
	v_mov_b32_dpp v117, v71 row_ror:15 row_mask:0xf bank_mask:0xf
	s_waitcnt vmcnt(5)
	v_mov_b32_dpp v83, v68 row_ror:1 row_mask:0xf bank_mask:0xf
	v_mov_b32_dpp v84, v69 row_ror:1 row_mask:0xf bank_mask:0xf
	v_mov_b32_dpp v101, v68 row_ror:15 row_mask:0xf bank_mask:0xf
	v_mov_b32_dpp v102, v69 row_ror:15 row_mask:0xf bank_mask:0xf
	v_mov_b32_dpp v86, v106 row_ror:1 row_mask:0xf bank_mask:0xf
	v_mov_b32_dpp v88, v107 row_ror:1 row_mask:0xf bank_mask:0xf
	v_mov_b32_dpp v85, v106 row_ror:15 row_mask:0xf bank_mask:0xf
	v_mov_b32_dpp v87, v107 row_ror:15 row_mask:0xf bank_mask:0xf
	v_cndmask_b32_e64 v43, 0, 1, s[86:87]
	v_mov_b32_e32 v42, 0
	v_cmp_ne_u32_e64 s[58:59], 1, v43
	s_andn2_b64 vcc, exec, s[86:87]
	v_mov_b32_e32 v78, 0
	v_mov_b32_e32 v79, 0
	s_cbranch_vccnz .LBB0_461
	ds_read_b64 v[78:79], v220

; __device__ __forceinline__ unsigned cvt_pk_bf16(float lo, float hi) { return pk2(lo, hi); }
;     __device__ __forceinline__ void operator()(f32x4 (&acc)[2][2][4][2], const Unit& u, int wr, int wc, int fr, int fq) const {
;     ...
;                     for (int m = 0; m < 4; ++m) {
;                         const f32x2 pvm = f0 ? (m == 0 ? pe : ps[m == 0 ? 0 : m - 1]) : ps[m];
;                         const f32x2 nvm = f15 ? (m == 3 ? ne : ns[m == 3 ? 3 : m + 1]) : ns[m];
;                         f32x2 cu = w1 * c[m] + bb; cu = w0 * pvm + cu; cu = w2 * nvm + cu;
;                         f32x2 tq = (cu * cu) * cu; tq = tq * 0.044715f + cu;
;                         const f32x2 ea = tq * (-2.3022082f);
;                         f32x2 dn; dn.x = __builtin_amdgcn_exp2f(ea.x); dn.y = __builtin_amdgcn_exp2f(ea.y); dn = dn + 1.0f;
;                         f32x2 rc; rc.x = __builtin_amdgcn_rcpf(dn.x); rc.y = __builtin_amdgcn_rcpf(dn.y);
;                         const f32x2 vv = {acc[ai][1][m][n][2 * p], acc[ai][1][m][n][2 * p + 1]};
;                         const f32x2 o = (cu * rc) * vv;
;                         res[m][2 * p] = o.x; res[m][2 * p + 1] = o.y; }
;                 }
; #pragma unroll
;                 for (int m = 0; m < 4; ++m) { const int j = ai * 128 + wr * 64 + m * 16 + fr;
;                     u32x2 w; w.x = cvt_pk_bf16(res[m][0], res[m][1]); w.y = cvt_pk_bf16(res[m][2], res[m][3]);
;                     if (j >= 1 && j <= 254) *(u32x2*)(act + (size_t)(rowt + j) * FFN + colg + 4 * n) = w; }
.LBB0_468:
	v_mov_b32_e32 v126, v164
	v_mov_b32_e32 v127, v164
	s_waitcnt lgkmcnt(0)
	v_cndmask_b32_e64 v79, v115, v79, s[36:37]
	v_cndmask_b32_e64 v78, v47, v78, s[36:37]
	s_waitcnt vmcnt(0)
	v_pk_fma_f32 v[110:111], v[110:111], v[58:59], v[62:63]
	v_pk_mul_f32 v[40:41], v[40:41], v[126:127]
	v_cndmask_b32_e64 v127, v122, v117, s[38:39]
	v_cndmask_b32_e64 v126, v67, v116, s[38:39]
	v_pk_fma_f32 v[78:79], v[50:51], v[78:79], v[110:111]
	s_mov_b32 s24, 0x3d372713
	v_pk_fma_f32 v[78:79], v[54:55], v[126:127], v[78:79]
	s_mov_b32 s62, 0xc0135761
	v_pk_mul_f32 v[110:111], v[78:79], v[78:79]
	v_pk_mul_f32 v[38:39], v[38:39], v[164:165]
	v_pk_mul_f32 v[110:111], v[78:79], v[110:111]
	v_pk_fma_f32 v[112:113], v[112:113], v[60:61], v[64:65]
	v_pk_fma_f32 v[110:111], v[110:111], s[24:25], v[78:79] op_sel_hi:[1,0,1]
	s_movk_i32 s15, 0x1600
	v_pk_mul_f32 v[110:111], v[110:111], s[62:63] op_sel_hi:[1,0]
	s_nop 0
	v_exp_f32_e32 v110, v110
	v_exp_f32_e32 v111, v111
	s_nop 0
	v_pk_add_f32 v[110:111], v[110:111], 1.0 op_sel_hi:[1,0]
	s_nop 0
	v_rcp_f32_e32 v110, v110
	v_rcp_f32_e32 v111, v111
	s_nop 0
	v_pk_mul_f32 v[78:79], v[78:79], v[110:111]
	s_nop 0
	v_pk_mul_f32 v[38:39], v[38:39], v[78:79]
	v_cndmask_b32_e64 v79, v119, v81, s[36:37]
	v_cndmask_b32_e64 v78, v118, v80, s[36:37]
	v_pk_fma_f32 v[78:79], v[52:53], v[78:79], v[112:113]
	v_cndmask_b32_e64 v81, v124, v121, s[38:39]
	v_cndmask_b32_e64 v80, v123, v120, s[38:39]
	v_pk_fma_f32 v[78:79], v[56:57], v[80:81], v[78:79]
	s_nop 0
	v_pk_mul_f32 v[80:81], v[78:79], v[78:79]
	s_nop 0
	v_pk_mul_f32 v[80:81], v[78:79], v[80:81]
	s_nop 0
	v_pk_fma_f32 v[80:81], v[80:81], s[24:25], v[78:79] op_sel_hi:[1,0,1]
	s_nop 0
	v_pk_mul_f32 v[80:81], v[80:81], s[62:63] op_sel_hi:[1,0]
	s_nop 0
	v_exp_f32_e32 v80, v80
	v_exp_f32_e32 v81, v81
	s_nop 0
	v_pk_add_f32 v[80:81], v[80:81], 1.0 op_sel_hi:[1,0]
	s_nop 0
	v_rcp_f32_e32 v80, v80
	v_rcp_f32_e32 v81, v81
	s_nop 0
	v_pk_mul_f32 v[78:79], v[78:79], v[80:81]
	s_nop 0
	v_pk_mul_f32 v[40:41], v[40:41], v[78:79]
	s_nop 0
	v_cvt_pk_bf16_f32 v41, v40, v41
	v_cvt_pk_bf16_f32 v40, v38, v39
	v_mov_b64_e32 v[38:39], s[76:77]
	v_mad_i64_i32 v[38:39], s[62:63], v82, s15, v[38:39]
	v_lshl_add_u64 v[38:39], v[162:163], 1, v[38:39]
	global_store_dwordx2 v[38:39], v[40:41], off
.LBB0_469:
	s_or_b64 exec, exec, s[12:13]
	v_mov_b32_e32 v67, v66
	s_waitcnt lgkmcnt(0)
	v_add_u32_e32 v78, s2, v214
	s_and_saveexec_b64 s[12:13], s[50:51]
	s_cbranch_execz .LBB0_471
	v_mov_b32_e32 v38, v66
	v_mov_b32_e32 v39, v66
	v_pk_mul_f32 v[36:37], v[36:37], v[38:39]
	s_waitcnt vmcnt(0)
	v_pk_fma_f32 v[38:39], v[72:73], v[60:61], v[64:65]
	v_pk_fma_f32 v[40:41], v[70:71], v[58:59], v[62:63]
	s_waitcnt lgkmcnt(0)
	v_cndmask_b32_e64 v70, v103, v118, s[36:37]
	v_cndmask_b32_e64 v71, v104, v119, s[36:37]
	v_cndmask_b32_e64 v72, v120, v105, s[38:39]
	v_cndmask_b32_e64 v73, v121, v114, s[38:39]
	v_pk_fma_f32 v[38:39], v[52:53], v[70:71], v[38:39]
	s_mov_b32 s24, 0x3d372713
	v_pk_fma_f32 v[38:39], v[56:57], v[72:73], v[38:39]
	s_mov_b32 s62, 0xc0135761
	v_pk_mul_f32 v[70:71], v[38:39], v[38:39]
	v_pk_mul_f32 v[34:35], v[34:35], v[66:67]
	v_pk_mul_f32 v[70:71], v[38:39], v[70:71]
	s_movk_i32 s15, 0x1600
	v_pk_fma_f32 v[70:71], v[70:71], s[24:25], v[38:39] op_sel_hi:[1,0,1]
	s_nop 0
	v_pk_mul_f32 v[70:71], v[70:71], s[62:63] op_sel_hi:[1,0]
	s_nop 0
	v_exp_f32_e32 v70, v70
	v_exp_f32_e32 v71, v71
	s_nop 0
	v_pk_add_f32 v[70:71], v[70:71], 1.0 op_sel_hi:[1,0]
	s_nop 0
	v_rcp_f32_e32 v70, v70
	v_rcp_f32_e32 v71, v71
	s_nop 0
	v_pk_mul_f32 v[38:39], v[38:39], v[70:71]
	s_nop 0
	v_pk_mul_f32 v[36:37], v[36:37], v[38:39]
	v_cndmask_b32_e64 v38, v99, v47, s[36:37]
	v_cndmask_b32_e64 v39, v100, v115, s[36:37]
	v_cndmask_b32_e64 v70, v116, v101, s[38:39]
	v_cndmask_b32_e64 v71, v117, v102, s[38:39]
	v_pk_fma_f32 v[38:39], v[50:51], v[38:39], v[40:41]
	v_cvt_pk_bf16_f32 v37, v36, v37
	v_pk_fma_f32 v[38:39], v[54:55], v[70:71], v[38:39]
	s_nop 0
	v_pk_mul_f32 v[40:41], v[38:39], v[38:39]
	s_nop 0
	v_pk_mul_f32 v[40:41], v[38:39], v[40:41]
	s_nop 0
	v_pk_fma_f32 v[40:41], v[40:41], s[24:25], v[38:39] op_sel_hi:[1,0,1]
	s_nop 0
	v_pk_mul_f32 v[40:41], v[40:41], s[62:63] op_sel_hi:[1,0]
	s_nop 0
	v_exp_f32_e32 v40, v40
	v_exp_f32_e32 v41, v41
	s_nop 0
	v_pk_add_f32 v[40:41], v[40:41], 1.0 op_sel_hi:[1,0]
	s_nop 0
	v_rcp_f32_e32 v40, v40
	v_rcp_f32_e32 v41, v41
	s_nop 0
	v_pk_mul_f32 v[38:39], v[38:39], v[40:41]
	s_nop 0
	v_pk_mul_f32 v[34:35], v[34:35], v[38:39]
	s_nop 0
	v_cvt_pk_bf16_f32 v36, v34, v35
	v_mov_b64_e32 v[34:35], s[76:77]
	v_mad_i64_i32 v[34:35], s[62:63], v78, s15, v[34:35]
	v_lshl_add_u64 v[34:35], v[162:163], 1, v[34:35]
	global_store_dwordx2 v[34:35], v[36:37], off
; __device__ __forceinline__ unsigned cvt_pk_bf16(float lo, float hi) { return pk2(lo, hi); }
;     __device__ __forceinline__ void operator()(f32x4 (&acc)[2][2][4][2], const Unit& u, int wr, int wc, int fr, int fq) const {
;     ...
;                     for (int m = 0; m < 4; ++m) {
;                         const f32x2 pvm = f0 ? (m == 0 ? pe : ps[m == 0 ? 0 : m - 1]) : ps[m];
;                         const f32x2 nvm = f15 ? (m == 3 ? ne : ns[m == 3 ? 3 : m + 1]) : ns[m];
;                         f32x2 cu = w1 * c[m] + bb; cu = w0 * pvm + cu; cu = w2 * nvm + cu;
;                         f32x2 tq = (cu * cu) * cu; tq = tq * 0.044715f + cu;
;                         const f32x2 ea = tq * (-2.3022082f);
;                         f32x2 dn; dn.x = __builtin_amdgcn_exp2f(ea.x); dn.y = __builtin_amdgcn_exp2f(ea.y); dn = dn + 1.0f;
;                         f32x2 rc; rc.x = __builtin_amdgcn_rcpf(dn.x); rc.y = __builtin_amdgcn_rcpf(dn.y);
;                         const f32x2 vv = {acc[ai][1][m][n][2 * p], acc[ai][1][m][n][2 * p + 1]};
;                         const f32x2 o = (cu * rc) * vv;
;                         res[m][2 * p] = o.x; res[m][2 * p + 1] = o.y; }
;                 }
; #pragma unroll
;                 for (int m = 0; m < 4; ++m) { const int j = ai * 128 + wr * 64 + m * 16 + fr;
;                     u32x2 w; w.x = cvt_pk_bf16(res[m][0], res[m][1]); w.y = cvt_pk_bf16(res[m][2], res[m][3]);
;                     if (j >= 1 && j <= 254) *(u32x2*)(act + (size_t)(rowt + j) * FFN + colg + 4 * n) = w; }
.LBB0_471:
	s_or_b64 exec, exec, s[12:13]
	v_mov_b32_e32 v47, v46
	v_add_u32_e32 v70, s2, v215
	s_and_saveexec_b64 s[12:13], s[52:53]
	s_cbranch_execz .LBB0_473
	v_mov_b32_e32 v34, v46
	v_mov_b32_e32 v35, v46
	v_pk_mul_f32 v[32:33], v[32:33], v[34:35]
	s_waitcnt vmcnt(0)
	v_pk_fma_f32 v[34:35], v[48:49], v[60:61], v[64:65]
	s_waitcnt lgkmcnt(0)
	v_cndmask_b32_e64 v38, v89, v103, s[36:37]
	v_cndmask_b32_e64 v39, v94, v104, s[36:37]
	v_cndmask_b32_e64 v40, v105, v95, s[38:39]
	v_cndmask_b32_e64 v41, v114, v97, s[38:39]
	v_pk_fma_f32 v[34:35], v[52:53], v[38:39], v[34:35]
	s_mov_b32 s24, 0x3d372713
	v_pk_fma_f32 v[34:35], v[56:57], v[40:41], v[34:35]
	s_mov_b32 s62, 0xc0135761
	v_pk_mul_f32 v[38:39], v[34:35], v[34:35]
	v_pk_fma_f32 v[36:37], v[68:69], v[58:59], v[62:63]
	v_pk_mul_f32 v[38:39], v[34:35], v[38:39]
	v_pk_mul_f32 v[30:31], v[30:31], v[46:47]
	v_pk_fma_f32 v[38:39], v[38:39], s[24:25], v[34:35] op_sel_hi:[1,0,1]
	s_movk_i32 s15, 0x1600
	v_pk_mul_f32 v[38:39], v[38:39], s[62:63] op_sel_hi:[1,0]
	s_nop 0
	v_exp_f32_e32 v38, v38
	v_exp_f32_e32 v39, v39
	s_nop 0
	v_pk_add_f32 v[38:39], v[38:39], 1.0 op_sel_hi:[1,0]
	s_nop 0
	v_rcp_f32_e32 v38, v38
	v_rcp_f32_e32 v39, v39
	s_nop 0
	v_pk_mul_f32 v[34:35], v[34:35], v[38:39]
	s_nop 0
	v_pk_mul_f32 v[32:33], v[32:33], v[34:35]
	v_cndmask_b32_e64 v34, v83, v99, s[36:37]
	v_cndmask_b32_e64 v35, v84, v100, s[36:37]
	v_cndmask_b32_e64 v38, v101, v85, s[38:39]
	v_cndmask_b32_e64 v39, v102, v87, s[38:39]
	v_pk_fma_f32 v[34:35], v[50:51], v[34:35], v[36:37]
	v_cvt_pk_bf16_f32 v33, v32, v33
	v_pk_fma_f32 v[34:35], v[54:55], v[38:39], v[34:35]
	s_nop 0
	v_pk_mul_f32 v[36:37], v[34:35], v[34:35]
	s_nop 0
	v_pk_mul_f32 v[36:37], v[34:35], v[36:37]
	s_nop 0
	v_pk_fma_f32 v[36:37], v[36:37], s[24:25], v[34:35] op_sel_hi:[1,0,1]
	s_nop 0
	v_pk_mul_f32 v[36:37], v[36:37], s[62:63] op_sel_hi:[1,0]
	s_nop 0
	v_exp_f32_e32 v36, v36
	v_exp_f32_e32 v37, v37
	s_nop 0
	v_pk_add_f32 v[36:37], v[36:37], 1.0 op_sel_hi:[1,0]
	s_nop 0
	v_rcp_f32_e32 v36, v36
	v_rcp_f32_e32 v37, v37
	s_nop 0
	v_pk_mul_f32 v[34:35], v[34:35], v[36:37]
	s_nop 0
	v_pk_mul_f32 v[30:31], v[30:31], v[34:35]
	s_nop 0
	v_cvt_pk_bf16_f32 v32, v30, v31
	v_mov_b64_e32 v[30:31], s[76:77]
	v_mad_i64_i32 v[30:31], s[62:63], v70, s15, v[30:31]
	v_lshl_add_u64 v[30:31], v[162:163], 1, v[30:31]
	global_store_dwordx2 v[30:31], v[32:33], off
.LBB0_473:
	s_or_b64 exec, exec, s[12:13]
	v_add_u32_e32 v68, s2, v216
	s_and_saveexec_b64 s[12:13], s[54:55]
	s_cbranch_execz .LBB0_475
	v_mov_b32_e32 v30, v160
	v_mov_b32_e32 v31, v160
	v_pk_mul_f32 v[28:29], v[28:29], v[30:31]
	s_waitcnt vmcnt(0)
	v_pk_fma_f32 v[30:31], v[108:109], v[60:61], v[64:65]
	s_waitcnt lgkmcnt(0)
	v_cndmask_b32_e64 v35, v98, v94, s[36:37]
	v_cndmask_b32_e64 v34, v96, v89, s[36:37]
	v_cndmask_b32_e64 v37, v97, v45, s[38:39]
	v_cndmask_b32_e64 v36, v95, v44, s[38:39]
	v_pk_fma_f32 v[30:31], v[52:53], v[34:35], v[30:31]
	s_mov_b32 s2, 0x3d372713
	v_pk_fma_f32 v[30:31], v[56:57], v[36:37], v[30:31]
	s_mov_b32 s24, 0xc0135761
	v_pk_mul_f32 v[34:35], v[30:31], v[30:31]
	v_pk_fma_f32 v[32:33], v[106:107], v[58:59], v[62:63]
	v_pk_mul_f32 v[34:35], v[30:31], v[34:35]
	v_pk_mul_f32 v[26:27], v[26:27], v[160:161]
	v_pk_fma_f32 v[34:35], v[34:35], s[2:3], v[30:31] op_sel_hi:[1,0,1]
	s_nop 0
	v_pk_mul_f32 v[34:35], v[34:35], s[24:25] op_sel_hi:[1,0]
	s_nop 0
	v_exp_f32_e32 v34, v34
	v_exp_f32_e32 v35, v35
	s_nop 0
	v_pk_add_f32 v[34:35], v[34:35], 1.0 op_sel_hi:[1,0]
	s_nop 0
	v_rcp_f32_e32 v34, v34
	v_rcp_f32_e32 v35, v35
	s_nop 0
	v_pk_mul_f32 v[30:31], v[30:31], v[34:35]
	s_nop 0
	v_pk_mul_f32 v[28:29], v[28:29], v[30:31]
	v_cndmask_b32_e64 v31, v88, v84, s[36:37]
	v_cndmask_b32_e64 v30, v86, v83, s[36:37]
	v_cndmask_b32_e64 v35, v87, v43, s[38:39]
	v_cndmask_b32_e64 v34, v85, v42, s[38:39]
	v_pk_fma_f32 v[30:31], v[50:51], v[30:31], v[32:33]
	v_cvt_pk_bf16_f32 v29, v28, v29
	v_pk_fma_f32 v[30:31], v[54:55], v[34:35], v[30:31]
	s_nop 0
	v_pk_mul_f32 v[32:33], v[30:31], v[30:31]
	s_nop 0
	v_pk_mul_f32 v[32:33], v[30:31], v[32:33]
	s_nop 0
	v_pk_fma_f32 v[32:33], v[32:33], s[2:3], v[30:31] op_sel_hi:[1,0,1]
	s_movk_i32 s2, 0x1600
	v_pk_mul_f32 v[32:33], v[32:33], s[24:25] op_sel_hi:[1,0]
	s_nop 0
	v_exp_f32_e32 v32, v32
	v_exp_f32_e32 v33, v33
	s_nop 0
	v_pk_add_f32 v[32:33], v[32:33], 1.0 op_sel_hi:[1,0]
	s_nop 0
	v_rcp_f32_e32 v32, v32
	v_rcp_f32_e32 v33, v33
	s_nop 0
	v_pk_mul_f32 v[30:31], v[30:31], v[32:33]
	s_nop 0
	v_pk_mul_f32 v[26:27], v[26:27], v[30:31]
	s_nop 0
	v_cvt_pk_bf16_f32 v28, v26, v27
	v_mov_b64_e32 v[26:27], s[76:77]
	v_mad_i64_i32 v[26:27], s[62:63], v68, s2, v[26:27]
	v_lshl_add_u64 v[26:27], v[162:163], 1, v[26:27]
	global_store_dwordx2 v[26:27], v[28:29], off
